# lockstep loads: one workgroup barrier per dilated chunk before the next-chunk K/V loads, so the 8 waves request the shared d=1/d=4 rows together (L1 merge)
# speedup vs baseline: 1.0063x; 1.0063x over previous
.LBB0_676:
	s_barrier
	s_waitcnt lgkmcnt(9)
	v_add_u32_e32 v0, s2, v199
	v_mul_lo_u32 v0, v0, s3
	v_add_u32_e32 v0, s14, v0
	s_waitcnt lgkmcnt(8)
	v_add_u32_e32 v0, s10, v0
	s_lshl_b32 s0, s3, 14
	v_lshl_or_b32 v2, v0, 11, v225
	global_load_dwordx4 v[160:163], v2, s[40:41]
	global_load_dwordx4 v[164:167], v2, s[42:43]
	v_add_u32_e32 v3, s0, v2
	global_load_dwordx4 v[168:171], v3, s[40:41]
	global_load_dwordx4 v[172:175], v3, s[42:43]
	v_add_u32_e32 v4, s0, v3
	global_load_dwordx4 v[176:179], v4, s[40:41]
	global_load_dwordx4 v[180:183], v4, s[42:43]
	v_add_u32_e32 v5, s0, v4
	global_load_dwordx4 v[184:187], v5, s[40:41]
	global_load_dwordx4 v[188:191], v5, s[42:43]
